# P6: row-sum (rstd) partial sums prefetched into free registers during the peeled last K-iteration, epilogue moves them instead of loading
# baseline (speedup 1.0000x reference)
; #define PG8_STAGE(bufoff, gbase, voff) do { _Pragma("unroll") for (int _i = 0; _i < 2; ++_i) \
;         __builtin_amdgcn_global_load_lds((const unsigned*)((const char*)(gbase) + (voff)[_i]), (PG8_LAS unsigned*)(lds + (bufoff) + ldsw + _i * 8192), 16, 0, 0); } while (0)
; #define PG8_LDA(dst, b, h) do { _Pragma("unroll") for (int m = 0; m < 4; ++m) _Pragma("unroll") for (int k = 0; k < 2; ++k) dst[m][k] = *(const PG8_LAS bf16x8*)(lds + PG8_SA(b, h) + aoff + m * 2048 + k * 1024); } while (0)
; #define PG8_LDB(dst, b, h) do { _Pragma("unroll") for (int n = 0; n < 2; ++n) _Pragma("unroll") for (int k = 0; k < 2; ++k) dst[n][k] = *(const PG8_LAS bf16x8*)(lds + PG8_SB(b, h) + boff + n * 2048 + k * 1024); } while (0)
; #define PG8_MMA(ai, bj, At, Bt) do { __builtin_amdgcn_s_setprio(1); _Pragma("unroll") for (int m = 0; m < 4; ++m) _Pragma("unroll") for (int n = 0; n < 2; ++n) _Pragma("unroll") for (int k = 0; k < 2; ++k) \
;         acc[ai][bj][m][n] = __builtin_amdgcn_mfma_f32_16x16x32_bf16(Bt[n][k], At[m][k], acc[ai][bj][m][n], 0, 0, 0); __builtin_amdgcn_s_setprio(0); } while (0)
; #define PG8_WAIT_V(n) asm volatile("s_waitcnt vmcnt(" #n ")" ::: "memory")
; template <class Epi, class Sched, bool ALIGN_EPI = false, bool SP2 = false>
; __device__ __forceinline__ void gemm_phase(PG8_LAS unsigned char* lds, const Gemm g, const Sched& S, const Epi& E) {
;     ...
;             PG8_LDB(B0, 0, 0); PG8_LDB(B1, 0, 1); PG8_SCHED; PG8_LDA(At, 0, 0); PG8_STAGE(PG8_SA(1, 1), a1 + hstep, voffA);
;             PG8_WAIT_V(8); PG8_WAIT_L(0); PG8_BAR; PG8_MMA(0, 0, At, B0); PG8_MMA(0, 1, At, B1); PG8_BAR; PG8_SCHED;
;             PG8_LDA(At, 0, 1); PG8_STAGE(PG8_SB(0, 0), b2, voffB); PG8_STAGE(PG8_SB(0, 1), b2 + hstep, voffB); PG8_STAGE(PG8_SA(0, 0), a2, voffA);
;             PG8_WAIT_V(8); PG8_WAIT_L(0); PG8_BAR; PG8_MMA(1, 0, At, B0); PG8_MMA(1, 1, At, B1); PG8_BAR; PG8_SCHED;
;             PG8_LDB(B0, 1, 0); PG8_LDB(B1, 1, 1); PG8_SCHED; PG8_LDA(At, 1, 0); PG8_STAGE(PG8_SA(0, 1), a2 + hstep, voffA);
;             PG8_WAIT_V(8); PG8_WAIT_L(0); PG8_BAR; PG8_MMA(0, 0, At, B0); PG8_MMA(0, 1, At, B1); PG8_BAR; PG8_SCHED;
;             PG8_LDA(At, 1, 1); PG8_STAGE(PG8_SB(1, 0), b3, voffB); PG8_STAGE(PG8_SB(1, 1), b3 + hstep, voffB); PG8_STAGE(PG8_SA(1, 0), a3, voffA);
;             PG8_WAIT_V(8); PG8_WAIT_L(0); PG8_BAR; PG8_MMA(1, 0, At, B0); PG8_MMA(1, 1, At, B1); PG8_BAR; PG8_SCHED;
.LBB0_1033:
	ds_read_b128 v[128:131], v202
	ds_read_b128 v[132:135], v202 offset:1024
	ds_read_b128 v[136:139], v202 offset:2048
	ds_read_b128 v[140:143], v202 offset:3072
	ds_read_b128 v[144:147], v203
	ds_read_b128 v[148:151], v203 offset:1024
	ds_read_b128 v[152:155], v203 offset:2048
	ds_read_b128 v[156:159], v203 offset:3072
	s_add_u32 s6, s4, 0xfffc0080
	s_addc_u32 s7, s5, -1
	s_cmp_eq_u32 s62, 12
	s_cselect_b32 s41, s3, s7
	s_cselect_b32 s40, s35, s6
	s_cselect_b32 s7, s31, s61
	s_cselect_b32 s6, s59, s60
	v_lshl_add_u64 v[218:219], s[4:5], 0, v[170:171]
	s_add_i32 m0, s44, 0xc000
	ds_read_b128 v[178:181], v204
	ds_read_b128 v[182:185], v204 offset:1024
	ds_read_b128 v[186:189], v204 offset:2048
	ds_read_b128 v[190:193], v204 offset:3072
	ds_read_b128 v[194:197], v204 offset:4096
	ds_read_b128 v[206:209], v204 offset:5120
	ds_read_b128 v[210:213], v204 offset:6144
	ds_read_b128 v[214:217], v204 offset:7168
	global_load_lds_dwordx4 v[218:219], off
	v_lshl_add_u64 v[218:219], s[4:5], 0, v[172:173]
	s_add_i32 m0, s44, 0xe000
	s_nop 0
	global_load_lds_dwordx4 v[218:219], off
	s_waitcnt vmcnt(8)
	s_waitcnt lgkmcnt(0)
	s_setprio 1
	s_barrier
	s_waitcnt lgkmcnt(0)
	v_mfma_f32_16x16x32_bf16 v[124:127], v[128:131], v[178:181], v[124:127]
	v_mfma_f32_16x16x32_bf16 v[120:123], v[136:139], v[178:181], v[120:123]
	v_mfma_f32_16x16x32_bf16 v[108:111], v[128:131], v[186:189], v[108:111]
	v_mfma_f32_16x16x32_bf16 v[104:107], v[136:139], v[186:189], v[104:107]
	v_mfma_f32_16x16x32_bf16 v[92:95], v[128:131], v[194:197], v[92:95]
	v_mfma_f32_16x16x32_bf16 v[88:91], v[136:139], v[194:197], v[88:91]
	v_mfma_f32_16x16x32_bf16 v[76:79], v[128:131], v[210:213], v[76:79]
	v_mfma_f32_16x16x32_bf16 v[72:75], v[136:139], v[210:213], v[72:75]
	v_mfma_f32_16x16x32_bf16 v[124:127], v[132:135], v[182:185], v[124:127]
	v_mfma_f32_16x16x32_bf16 v[120:123], v[140:143], v[182:185], v[120:123]
	v_mfma_f32_16x16x32_bf16 v[108:111], v[132:135], v[190:193], v[108:111]
	v_mfma_f32_16x16x32_bf16 v[104:107], v[140:143], v[190:193], v[104:107]
	v_mfma_f32_16x16x32_bf16 v[92:95], v[132:135], v[206:209], v[92:95]
	v_mfma_f32_16x16x32_bf16 v[88:91], v[140:143], v[206:209], v[88:91]
	v_mfma_f32_16x16x32_bf16 v[76:79], v[132:135], v[214:217], v[76:79]
	v_mfma_f32_16x16x32_bf16 v[72:75], v[140:143], v[214:217], v[72:75]
	s_setprio 0
	s_setprio 1
	v_mfma_f32_16x16x32_bf16 v[116:119], v[144:147], v[178:181], v[116:119]
	v_mfma_f32_16x16x32_bf16 v[112:115], v[152:155], v[178:181], v[112:115]
	v_mfma_f32_16x16x32_bf16 v[100:103], v[144:147], v[186:189], v[100:103]
	v_mfma_f32_16x16x32_bf16 v[96:99], v[152:155], v[186:189], v[96:99]
	v_mfma_f32_16x16x32_bf16 v[84:87], v[144:147], v[194:197], v[84:87]
	v_mfma_f32_16x16x32_bf16 v[80:83], v[152:155], v[194:197], v[80:83]
	v_mfma_f32_16x16x32_bf16 v[68:71], v[144:147], v[210:213], v[68:71]
	v_mfma_f32_16x16x32_bf16 v[64:67], v[152:155], v[210:213], v[64:67]
	v_mfma_f32_16x16x32_bf16 v[116:119], v[148:151], v[182:185], v[116:119]
	v_mfma_f32_16x16x32_bf16 v[112:115], v[156:159], v[182:185], v[112:115]
	v_mfma_f32_16x16x32_bf16 v[100:103], v[148:151], v[190:193], v[100:103]
	v_mfma_f32_16x16x32_bf16 v[96:99], v[156:159], v[190:193], v[96:99]
	v_mfma_f32_16x16x32_bf16 v[84:87], v[148:151], v[206:209], v[84:87]
	v_mfma_f32_16x16x32_bf16 v[80:83], v[156:159], v[206:209], v[80:83]
	v_mfma_f32_16x16x32_bf16 v[68:71], v[148:151], v[214:217], v[68:71]
	s_setprio 3
	s_barrier
	v_mfma_f32_16x16x32_bf16 v[64:67], v[156:159], v[214:217], v[64:67]
	s_setprio 0
	s_add_i32 s63, s55, s42
	v_lshl_add_u64 v[218:219], s[6:7], 0, v[162:163]
	s_mov_b32 m0, s63
	ds_read_b128 v[178:181], v204 offset:16384
	ds_read_b128 v[182:185], v204 offset:17408
	ds_read_b128 v[186:189], v204 offset:18432
	ds_read_b128 v[190:193], v204 offset:19456
	ds_read_b128 v[194:197], v204 offset:20480
	ds_read_b128 v[206:209], v204 offset:21504
	ds_read_b128 v[210:213], v204 offset:22528
	ds_read_b128 v[214:217], v204 offset:23552
	global_load_lds_dwordx4 v[218:219], off
	s_add_i32 m0, s63, 0x2000
	s_add_u32 s64, s6, 0x40000
	v_lshl_add_u64 v[220:221], s[6:7], 0, v[166:167]
	s_addc_u32 s65, s7, 0
	s_add_i32 s63, s56, s42
	global_load_lds_dwordx4 v[220:221], off
	v_lshl_add_u64 v[222:223], s[64:65], 0, v[162:163]
	s_mov_b32 m0, s63
	v_lshl_add_u64 v[224:225], s[40:41], 0, v[164:165]
	global_load_lds_dwordx4 v[222:223], off
	v_lshl_add_u64 v[222:223], s[64:65], 0, v[166:167]
	s_add_i32 m0, s63, 0x2000
	s_nop 0
	global_load_lds_dwordx4 v[222:223], off
	v_lshl_add_u64 v[222:223], s[40:41], 0, v[160:161]
	s_mov_b32 m0, s44
	s_nop 0
	global_load_lds_dwordx4 v[222:223], off
	s_mov_b32 m0, s45
	s_nop 0
	global_load_lds_dwordx4 v[224:225], off
	s_waitcnt vmcnt(8)
	s_waitcnt lgkmcnt(0)
	s_setprio 1
	s_barrier
; #define PG8_STAGE(bufoff, gbase, voff) do { _Pragma("unroll") for (int _i = 0; _i < 2; ++_i) \
;         __builtin_amdgcn_global_load_lds((const unsigned*)((const char*)(gbase) + (voff)[_i]), (PG8_LAS unsigned*)(lds + (bufoff) + ldsw + _i * 8192), 16, 0, 0); } while (0)
; #define PG8_LDA(dst, b, h) do { _Pragma("unroll") for (int m = 0; m < 4; ++m) _Pragma("unroll") for (int k = 0; k < 2; ++k) dst[m][k] = *(const PG8_LAS bf16x8*)(lds + PG8_SA(b, h) + aoff + m * 2048 + k * 1024); } while (0)
; #define PG8_LDB(dst, b, h) do { _Pragma("unroll") for (int n = 0; n < 2; ++n) _Pragma("unroll") for (int k = 0; k < 2; ++k) dst[n][k] = *(const PG8_LAS bf16x8*)(lds + PG8_SB(b, h) + boff + n * 2048 + k * 1024); } while (0)
; #define PG8_MMA(ai, bj, At, Bt) do { __builtin_amdgcn_s_setprio(1); _Pragma("unroll") for (int m = 0; m < 4; ++m) _Pragma("unroll") for (int n = 0; n < 2; ++n) _Pragma("unroll") for (int k = 0; k < 2; ++k) \
;         acc[ai][bj][m][n] = __builtin_amdgcn_mfma_f32_16x16x32_bf16(Bt[n][k], At[m][k], acc[ai][bj][m][n], 0, 0, 0); __builtin_amdgcn_s_setprio(0); } while (0)
; #define PG8_WAIT_V(n) asm volatile("s_waitcnt vmcnt(" #n ")" ::: "memory")
; template <class Epi, class Sched, bool ALIGN_EPI = false, bool SP2 = false>
; __device__ __forceinline__ void gemm_phase(PG8_LAS unsigned char* lds, const Gemm g, const Sched& S, const Epi& E) {
;     ...
;             PG8_LDB(B0, 0, 0); PG8_LDB(B1, 0, 1); PG8_SCHED; PG8_LDA(At, 0, 0); PG8_STAGE(PG8_SA(1, 1), a1 + hstep, voffA);
;             PG8_WAIT_V(8); PG8_WAIT_L(0); PG8_BAR; PG8_MMA(0, 0, At, B0); PG8_MMA(0, 1, At, B1); PG8_BAR; PG8_SCHED;
;             PG8_LDA(At, 0, 1); PG8_STAGE(PG8_SB(0, 0), b2, voffB); PG8_STAGE(PG8_SB(0, 1), b2 + hstep, voffB); PG8_STAGE(PG8_SA(0, 0), a2, voffA);
;             PG8_WAIT_V(8); PG8_WAIT_L(0); PG8_BAR; PG8_MMA(1, 0, At, B0); PG8_MMA(1, 1, At, B1); PG8_BAR; PG8_SCHED;
;             PG8_LDB(B0, 1, 0); PG8_LDB(B1, 1, 1); PG8_SCHED; PG8_LDA(At, 1, 0); PG8_STAGE(PG8_SA(0, 1), a2 + hstep, voffA);
;             PG8_WAIT_V(8); PG8_WAIT_L(0); PG8_BAR; PG8_MMA(0, 0, At, B0); PG8_MMA(0, 1, At, B1); PG8_BAR; PG8_SCHED;
;             PG8_LDA(At, 1, 1); PG8_STAGE(PG8_SB(1, 0), b3, voffB); PG8_STAGE(PG8_SB(1, 1), b3 + hstep, voffB); PG8_STAGE(PG8_SA(1, 0), a3, voffA);
;             PG8_WAIT_V(8); PG8_WAIT_L(0); PG8_BAR; PG8_MMA(1, 0, At, B0); PG8_MMA(1, 1, At, B1); PG8_BAR; PG8_SCHED;
	s_waitcnt lgkmcnt(0)
	v_mfma_f32_16x16x32_bf16 v[60:63], v[128:131], v[178:181], v[60:63]
	v_mfma_f32_16x16x32_bf16 v[56:59], v[136:139], v[178:181], v[56:59]
	v_mfma_f32_16x16x32_bf16 v[44:47], v[128:131], v[186:189], v[44:47]
	v_mfma_f32_16x16x32_bf16 v[40:43], v[136:139], v[186:189], v[40:43]
	v_mfma_f32_16x16x32_bf16 v[28:31], v[128:131], v[194:197], v[28:31]
	v_mfma_f32_16x16x32_bf16 v[24:27], v[136:139], v[194:197], v[24:27]
	v_mfma_f32_16x16x32_bf16 v[12:15], v[128:131], v[210:213], v[12:15]
	v_mfma_f32_16x16x32_bf16 v[8:11], v[136:139], v[210:213], v[8:11]
	v_mfma_f32_16x16x32_bf16 v[60:63], v[132:135], v[182:185], v[60:63]
	v_mfma_f32_16x16x32_bf16 v[56:59], v[140:143], v[182:185], v[56:59]
	v_mfma_f32_16x16x32_bf16 v[44:47], v[132:135], v[190:193], v[44:47]
	v_mfma_f32_16x16x32_bf16 v[40:43], v[140:143], v[190:193], v[40:43]
	v_mfma_f32_16x16x32_bf16 v[28:31], v[132:135], v[206:209], v[28:31]
	v_mfma_f32_16x16x32_bf16 v[24:27], v[140:143], v[206:209], v[24:27]
	v_mfma_f32_16x16x32_bf16 v[12:15], v[132:135], v[214:217], v[12:15]
	v_mfma_f32_16x16x32_bf16 v[8:11], v[140:143], v[214:217], v[8:11]
	s_setprio 0
	s_setprio 1
	v_mfma_f32_16x16x32_bf16 v[52:55], v[144:147], v[178:181], v[52:55]
	v_mfma_f32_16x16x32_bf16 v[48:51], v[152:155], v[178:181], v[48:51]
	v_mfma_f32_16x16x32_bf16 v[36:39], v[144:147], v[186:189], v[36:39]
	v_mfma_f32_16x16x32_bf16 v[32:35], v[152:155], v[186:189], v[32:35]
	v_mfma_f32_16x16x32_bf16 v[20:23], v[144:147], v[194:197], v[20:23]
	v_mfma_f32_16x16x32_bf16 v[16:19], v[152:155], v[194:197], v[16:19]
	v_mfma_f32_16x16x32_bf16 v[4:7], v[144:147], v[210:213], v[4:7]
	v_mfma_f32_16x16x32_bf16 v[0:3], v[152:155], v[210:213], v[0:3]
	v_mfma_f32_16x16x32_bf16 v[52:55], v[148:151], v[182:185], v[52:55]
	v_mfma_f32_16x16x32_bf16 v[48:51], v[156:159], v[182:185], v[48:51]
	v_mfma_f32_16x16x32_bf16 v[36:39], v[148:151], v[190:193], v[36:39]
	v_mfma_f32_16x16x32_bf16 v[32:35], v[156:159], v[190:193], v[32:35]
	v_mfma_f32_16x16x32_bf16 v[20:23], v[148:151], v[206:209], v[20:23]
	v_mfma_f32_16x16x32_bf16 v[16:19], v[156:159], v[206:209], v[16:19]
	v_mfma_f32_16x16x32_bf16 v[4:7], v[148:151], v[214:217], v[4:7]
	s_setprio 3
	s_barrier
	v_mfma_f32_16x16x32_bf16 v[0:3], v[156:159], v[214:217], v[0:3]
	s_setprio 0
	s_add_i32 s63, 0, 0x18000
	s_add_i32 s64, 0, 0x1c000
	v_add_u32_e32 v140, s63, v199
	v_add_u32_e32 v156, s64, v199
	ds_read_b128 v[128:131], v140
	ds_read_b128 v[132:135], v140 offset:1024
	ds_read_b128 v[136:139], v140 offset:2048
	ds_read_b128 v[140:143], v140 offset:3072
	ds_read_b128 v[144:147], v156
	ds_read_b128 v[148:151], v156 offset:1024
	ds_read_b128 v[152:155], v156 offset:2048
	ds_read_b128 v[156:159], v156 offset:3072
	s_add_u32 s40, s40, 0x40000
	s_addc_u32 s41, s41, 0
	s_mov_b32 m0, s46
	v_lshl_add_u64 v[226:227], s[40:41], 0, v[160:161]
	ds_read_b128 v[178:181], v204 offset:32768
	ds_read_b128 v[182:185], v204 offset:33792
	ds_read_b128 v[186:189], v204 offset:34816
	ds_read_b128 v[190:193], v204 offset:35840
	ds_read_b128 v[194:197], v204 offset:36864
	ds_read_b128 v[206:209], v204 offset:37888
	ds_read_b128 v[210:213], v204 offset:38912
	ds_read_b128 v[214:217], v204 offset:39936
	global_load_lds_dwordx4 v[226:227], off
	v_lshl_add_u64 v[226:227], s[40:41], 0, v[164:165]
	s_mov_b32 m0, s47
	s_nop 0
	global_load_lds_dwordx4 v[226:227], off
	s_waitcnt vmcnt(8)
	s_waitcnt lgkmcnt(0)
	s_setprio 1
	s_barrier
	s_waitcnt lgkmcnt(0)
	v_mfma_f32_16x16x32_bf16 v[124:127], v[128:131], v[178:181], v[124:127]
	v_mfma_f32_16x16x32_bf16 v[120:123], v[136:139], v[178:181], v[120:123]
	v_mfma_f32_16x16x32_bf16 v[108:111], v[128:131], v[186:189], v[108:111]
	v_mfma_f32_16x16x32_bf16 v[104:107], v[136:139], v[186:189], v[104:107]
	v_mfma_f32_16x16x32_bf16 v[92:95], v[128:131], v[194:197], v[92:95]
	v_mfma_f32_16x16x32_bf16 v[88:91], v[136:139], v[194:197], v[88:91]
	v_mfma_f32_16x16x32_bf16 v[76:79], v[128:131], v[210:213], v[76:79]
	v_mfma_f32_16x16x32_bf16 v[72:75], v[136:139], v[210:213], v[72:75]
	v_mfma_f32_16x16x32_bf16 v[124:127], v[132:135], v[182:185], v[124:127]
	v_mfma_f32_16x16x32_bf16 v[120:123], v[140:143], v[182:185], v[120:123]
	v_mfma_f32_16x16x32_bf16 v[108:111], v[132:135], v[190:193], v[108:111]
	v_mfma_f32_16x16x32_bf16 v[104:107], v[140:143], v[190:193], v[104:107]
	v_mfma_f32_16x16x32_bf16 v[92:95], v[132:135], v[206:209], v[92:95]
	v_mfma_f32_16x16x32_bf16 v[88:91], v[140:143], v[206:209], v[88:91]
	v_mfma_f32_16x16x32_bf16 v[76:79], v[132:135], v[214:217], v[76:79]
	v_mfma_f32_16x16x32_bf16 v[72:75], v[140:143], v[214:217], v[72:75]
	s_setprio 0
	s_setprio 1
	v_mfma_f32_16x16x32_bf16 v[116:119], v[144:147], v[178:181], v[116:119]
	v_mfma_f32_16x16x32_bf16 v[112:115], v[152:155], v[178:181], v[112:115]
	v_mfma_f32_16x16x32_bf16 v[100:103], v[144:147], v[186:189], v[100:103]
	v_mfma_f32_16x16x32_bf16 v[96:99], v[152:155], v[186:189], v[96:99]
	v_mfma_f32_16x16x32_bf16 v[84:87], v[144:147], v[194:197], v[84:87]
	v_mfma_f32_16x16x32_bf16 v[80:83], v[152:155], v[194:197], v[80:83]
	v_mfma_f32_16x16x32_bf16 v[68:71], v[144:147], v[210:213], v[68:71]
	v_mfma_f32_16x16x32_bf16 v[64:67], v[152:155], v[210:213], v[64:67]
	v_mfma_f32_16x16x32_bf16 v[116:119], v[148:151], v[182:185], v[116:119]
	v_mfma_f32_16x16x32_bf16 v[112:115], v[156:159], v[182:185], v[112:115]
	v_mfma_f32_16x16x32_bf16 v[100:103], v[148:151], v[190:193], v[100:103]
	v_mfma_f32_16x16x32_bf16 v[96:99], v[156:159], v[190:193], v[96:99]
	v_mfma_f32_16x16x32_bf16 v[84:87], v[148:151], v[206:209], v[84:87]
	v_mfma_f32_16x16x32_bf16 v[80:83], v[156:159], v[206:209], v[80:83]
	v_mfma_f32_16x16x32_bf16 v[68:71], v[148:151], v[214:217], v[68:71]
	s_setprio 3
	s_barrier
; #define PG8_STAGE(bufoff, gbase, voff) do { _Pragma("unroll") for (int _i = 0; _i < 2; ++_i) \
;         __builtin_amdgcn_global_load_lds((const unsigned*)((const char*)(gbase) + (voff)[_i]), (PG8_LAS unsigned*)(lds + (bufoff) + ldsw + _i * 8192), 16, 0, 0); } while (0)
; #define PG8_LDA(dst, b, h) do { _Pragma("unroll") for (int m = 0; m < 4; ++m) _Pragma("unroll") for (int k = 0; k < 2; ++k) dst[m][k] = *(const PG8_LAS bf16x8*)(lds + PG8_SA(b, h) + aoff + m * 2048 + k * 1024); } while (0)
; #define PG8_LDB(dst, b, h) do { _Pragma("unroll") for (int n = 0; n < 2; ++n) _Pragma("unroll") for (int k = 0; k < 2; ++k) dst[n][k] = *(const PG8_LAS bf16x8*)(lds + PG8_SB(b, h) + boff + n * 2048 + k * 1024); } while (0)
; #define PG8_MMA(ai, bj, At, Bt) do { __builtin_amdgcn_s_setprio(1); _Pragma("unroll") for (int m = 0; m < 4; ++m) _Pragma("unroll") for (int n = 0; n < 2; ++n) _Pragma("unroll") for (int k = 0; k < 2; ++k) \
;         acc[ai][bj][m][n] = __builtin_amdgcn_mfma_f32_16x16x32_bf16(Bt[n][k], At[m][k], acc[ai][bj][m][n], 0, 0, 0); __builtin_amdgcn_s_setprio(0); } while (0)
; #define PG8_WAIT_V(n) asm volatile("s_waitcnt vmcnt(" #n ")" ::: "memory")
; template <class Epi, class Sched, bool ALIGN_EPI = false, bool SP2 = false>
; __device__ __forceinline__ void gemm_phase(PG8_LAS unsigned char* lds, const Gemm g, const Sched& S, const Epi& E) {
;     ...
;             PG8_LDB(B0, 0, 0); PG8_LDB(B1, 0, 1); PG8_SCHED; PG8_LDA(At, 0, 0); PG8_STAGE(PG8_SA(1, 1), a1 + hstep, voffA);
;             PG8_WAIT_V(8); PG8_WAIT_L(0); PG8_BAR; PG8_MMA(0, 0, At, B0); PG8_MMA(0, 1, At, B1); PG8_BAR; PG8_SCHED;
;             PG8_LDA(At, 0, 1); PG8_STAGE(PG8_SB(0, 0), b2, voffB); PG8_STAGE(PG8_SB(0, 1), b2 + hstep, voffB); PG8_STAGE(PG8_SA(0, 0), a2, voffA);
;             PG8_WAIT_V(8); PG8_WAIT_L(0); PG8_BAR; PG8_MMA(1, 0, At, B0); PG8_MMA(1, 1, At, B1); PG8_BAR; PG8_SCHED;
;             PG8_LDB(B0, 1, 0); PG8_LDB(B1, 1, 1); PG8_SCHED; PG8_LDA(At, 1, 0); PG8_STAGE(PG8_SA(0, 1), a2 + hstep, voffA);
;             PG8_WAIT_V(8); PG8_WAIT_L(0); PG8_BAR; PG8_MMA(0, 0, At, B0); PG8_MMA(0, 1, At, B1); PG8_BAR; PG8_SCHED;
;             PG8_LDA(At, 1, 1); PG8_STAGE(PG8_SB(1, 0), b3, voffB); PG8_STAGE(PG8_SB(1, 1), b3 + hstep, voffB); PG8_STAGE(PG8_SA(1, 0), a3, voffA);
;             PG8_WAIT_V(8); PG8_WAIT_L(0); PG8_BAR; PG8_MMA(1, 0, At, B0); PG8_MMA(1, 1, At, B1); PG8_BAR; PG8_SCHED;
	v_mfma_f32_16x16x32_bf16 v[64:67], v[156:159], v[214:217], v[64:67]
	s_setprio 0
	s_add_i32 s40, s63, s42
	v_lshl_add_u64 v[218:219], v[218:219], 0, s[12:13]
	s_mov_b32 m0, s40
	ds_read_b128 v[178:181], v204 offset:49152
	ds_read_b128 v[182:185], v204 offset:50176
	ds_read_b128 v[186:189], v204 offset:51200
	ds_read_b128 v[190:193], v204 offset:52224
	ds_read_b128 v[194:197], v204 offset:53248
	ds_read_b128 v[206:209], v204 offset:54272
	ds_read_b128 v[210:213], v204 offset:55296
	ds_read_b128 v[214:217], v204 offset:56320
	global_load_lds_dwordx4 v[218:219], off
	s_add_i32 m0, s40, 0x2000
	s_add_u32 s6, s6, 0x40080
	v_lshl_add_u64 v[218:219], v[220:221], 0, s[12:13]
	s_addc_u32 s7, s7, 0
	s_add_i32 s40, s64, s42
	global_load_lds_dwordx4 v[218:219], off
	v_lshl_add_u64 v[218:219], s[6:7], 0, v[162:163]
	s_mov_b32 m0, s40
	s_nop 0
	global_load_lds_dwordx4 v[218:219], off
	v_lshl_add_u64 v[218:219], s[6:7], 0, v[166:167]
	s_add_i32 m0, s40, 0x2000
	s_nop 0
	global_load_lds_dwordx4 v[218:219], off
	v_lshl_add_u64 v[218:219], v[222:223], 0, s[12:13]
	s_mov_b32 m0, s52
	s_nop 0
	global_load_lds_dwordx4 v[218:219], off
	v_lshl_add_u64 v[218:219], v[224:225], 0, s[12:13]
	s_mov_b32 m0, s53
	s_nop 0
	global_load_lds_dwordx4 v[218:219], off
	s_waitcnt vmcnt(8)
	s_waitcnt lgkmcnt(0)
	s_setprio 1
	s_barrier
	s_waitcnt lgkmcnt(0)
	v_mfma_f32_16x16x32_bf16 v[60:63], v[128:131], v[178:181], v[60:63]
	v_mfma_f32_16x16x32_bf16 v[56:59], v[136:139], v[178:181], v[56:59]
	v_mfma_f32_16x16x32_bf16 v[44:47], v[128:131], v[186:189], v[44:47]
	v_mfma_f32_16x16x32_bf16 v[40:43], v[136:139], v[186:189], v[40:43]
	v_mfma_f32_16x16x32_bf16 v[28:31], v[128:131], v[194:197], v[28:31]
	v_mfma_f32_16x16x32_bf16 v[24:27], v[136:139], v[194:197], v[24:27]
	v_mfma_f32_16x16x32_bf16 v[12:15], v[128:131], v[210:213], v[12:15]
	v_mfma_f32_16x16x32_bf16 v[8:11], v[136:139], v[210:213], v[8:11]
	v_mfma_f32_16x16x32_bf16 v[60:63], v[132:135], v[182:185], v[60:63]
	v_mfma_f32_16x16x32_bf16 v[56:59], v[140:143], v[182:185], v[56:59]
	v_mfma_f32_16x16x32_bf16 v[44:47], v[132:135], v[190:193], v[44:47]
	v_mfma_f32_16x16x32_bf16 v[40:43], v[140:143], v[190:193], v[40:43]
	v_mfma_f32_16x16x32_bf16 v[28:31], v[132:135], v[206:209], v[28:31]
	v_mfma_f32_16x16x32_bf16 v[24:27], v[140:143], v[206:209], v[24:27]
	v_mfma_f32_16x16x32_bf16 v[12:15], v[132:135], v[214:217], v[12:15]
	v_mfma_f32_16x16x32_bf16 v[8:11], v[140:143], v[214:217], v[8:11]
	s_setprio 0
	s_setprio 1
	v_mfma_f32_16x16x32_bf16 v[52:55], v[144:147], v[178:181], v[52:55]
	v_mfma_f32_16x16x32_bf16 v[48:51], v[152:155], v[178:181], v[48:51]
	v_mfma_f32_16x16x32_bf16 v[36:39], v[144:147], v[186:189], v[36:39]
	v_mfma_f32_16x16x32_bf16 v[32:35], v[152:155], v[186:189], v[32:35]
	v_mfma_f32_16x16x32_bf16 v[20:23], v[144:147], v[194:197], v[20:23]
	v_mfma_f32_16x16x32_bf16 v[16:19], v[152:155], v[194:197], v[16:19]
	v_mfma_f32_16x16x32_bf16 v[4:7], v[144:147], v[210:213], v[4:7]
	v_mfma_f32_16x16x32_bf16 v[0:3], v[152:155], v[210:213], v[0:3]
	v_mfma_f32_16x16x32_bf16 v[52:55], v[148:151], v[182:185], v[52:55]
	v_mfma_f32_16x16x32_bf16 v[48:51], v[156:159], v[182:185], v[48:51]
	v_mfma_f32_16x16x32_bf16 v[36:39], v[148:151], v[190:193], v[36:39]
	v_mfma_f32_16x16x32_bf16 v[32:35], v[156:159], v[190:193], v[32:35]
	v_mfma_f32_16x16x32_bf16 v[20:23], v[148:151], v[206:209], v[20:23]
	v_mfma_f32_16x16x32_bf16 v[16:19], v[156:159], v[206:209], v[16:19]
	v_mfma_f32_16x16x32_bf16 v[4:7], v[148:151], v[214:217], v[4:7]
	s_setprio 3
	s_barrier
	v_mfma_f32_16x16x32_bf16 v[0:3], v[156:159], v[214:217], v[0:3]
	s_setprio 0
	s_add_i32 s62, s62, 2
	s_add_u32 s4, s4, 0x100
	s_addc_u32 s5, s5, 0
	s_add_u32 s60, s60, 0x100
	s_addc_u32 s61, s61, 0
	s_cmp_gt_u32 s62, 13
	s_cbranch_scc1 .Lp6x_gen
	s_cmp_lg_u32 s62, 12
	s_cbranch_scc1 .LBB0_1033
	s_cmpk_lg_i32 s33, 0x100
	s_cbranch_scc1 .LBB0_1033
	ds_read_b128 v[128:131], v202
	ds_read_b128 v[132:135], v202 offset:1024
	ds_read_b128 v[136:139], v202 offset:2048
	ds_read_b128 v[140:143], v202 offset:3072
	ds_read_b128 v[144:147], v203
	ds_read_b128 v[148:151], v203 offset:1024
	ds_read_b128 v[152:155], v203 offset:2048
	ds_read_b128 v[156:159], v203 offset:3072
	s_add_u32 s6, s4, 0xfffc0080
	s_addc_u32 s7, s5, -1
	s_cmp_eq_u32 s62, 12
	s_cselect_b32 s41, s3, s7
	s_cselect_b32 s40, s35, s6
	s_cselect_b32 s7, s31, s61
	s_cselect_b32 s6, s59, s60
	v_lshl_add_u64 v[218:219], s[4:5], 0, v[170:171]
	s_add_i32 m0, s44, 0xc000
	ds_read_b128 v[178:181], v204
	ds_read_b128 v[182:185], v204 offset:1024
	ds_read_b128 v[186:189], v204 offset:2048
	ds_read_b128 v[190:193], v204 offset:3072
	ds_read_b128 v[194:197], v204 offset:4096
	ds_read_b128 v[206:209], v204 offset:5120
	ds_read_b128 v[210:213], v204 offset:6144
	ds_read_b128 v[214:217], v204 offset:7168
	global_load_lds_dwordx4 v[218:219], off
	v_lshl_add_u64 v[218:219], s[4:5], 0, v[172:173]
	s_add_i32 m0, s44, 0xe000
	s_nop 0
	global_load_lds_dwordx4 v[218:219], off
	s_waitcnt vmcnt(8)
	s_waitcnt lgkmcnt(0)
	s_setprio 1
	s_barrier
; #define PG8_STAGE(bufoff, gbase, voff) do { _Pragma("unroll") for (int _i = 0; _i < 2; ++_i) \
;         __builtin_amdgcn_global_load_lds((const unsigned*)((const char*)(gbase) + (voff)[_i]), (PG8_LAS unsigned*)(lds + (bufoff) + ldsw + _i * 8192), 16, 0, 0); } while (0)
; #define PG8_LDA(dst, b, h) do { _Pragma("unroll") for (int m = 0; m < 4; ++m) _Pragma("unroll") for (int k = 0; k < 2; ++k) dst[m][k] = *(const PG8_LAS bf16x8*)(lds + PG8_SA(b, h) + aoff + m * 2048 + k * 1024); } while (0)
; #define PG8_LDB(dst, b, h) do { _Pragma("unroll") for (int n = 0; n < 2; ++n) _Pragma("unroll") for (int k = 0; k < 2; ++k) dst[n][k] = *(const PG8_LAS bf16x8*)(lds + PG8_SB(b, h) + boff + n * 2048 + k * 1024); } while (0)
; #define PG8_WAIT_V(n) asm volatile("s_waitcnt vmcnt(" #n ")" ::: "memory")
; #define PG8_WAIT_L(n) asm volatile("s_waitcnt lgkmcnt(" #n ")" ::: "memory")
; __device__ __forceinline__ void row_rstd8(const float* SS, int row0, int fq, float (&rs)[2][4]) {
;     ...
;         for (int m = 0; m < 4; ++m) { const f32x4 t = *(const f32x4*)(SS + (size_t)(row0 + ai * HALF + m * 16) * 16 + 4 * fq); rs[ai][m] = (t[0] + t[1]) + (t[2] + t[3]); }
; template <class Epi, class Sched, bool ALIGN_EPI = false, bool SP2 = false>
; __device__ __forceinline__ void gemm_phase(PG8_LAS unsigned char* lds, const Gemm g, const Sched& S, const Epi& E) {
;     ...
;             PG8_LDB(B0, 0, 0); PG8_LDB(B1, 0, 1); PG8_SCHED; PG8_LDA(At, 0, 0); PG8_STAGE(PG8_SA(1, 1), a1 + hstep, voffA);
;             PG8_WAIT_V(8); PG8_WAIT_L(0); PG8_BAR; PG8_MMA(0, 0, At, B0); PG8_MMA(0, 1, At, B1); PG8_BAR; PG8_SCHED;
;             PG8_LDA(At, 0, 1); PG8_STAGE(PG8_SB(0, 0), b2, voffB); PG8_STAGE(PG8_SB(0, 1), b2 + hstep, voffB); PG8_STAGE(PG8_SA(0, 0), a2, voffA);
;             PG8_WAIT_V(8); PG8_WAIT_L(0); PG8_BAR; PG8_MMA(1, 0, At, B0); PG8_MMA(1, 1, At, B1); PG8_BAR; PG8_SCHED;
;             PG8_LDB(B0, 1, 0); PG8_LDB(B1, 1, 1); PG8_SCHED; PG8_LDA(At, 1, 0); PG8_STAGE(PG8_SA(0, 1), a2 + hstep, voffA);
;             PG8_WAIT_V(8); PG8_WAIT_L(0); PG8_BAR; PG8_MMA(0, 0, At, B0); PG8_MMA(0, 1, At, B1); PG8_BAR; PG8_SCHED;
;             PG8_LDA(At, 1, 1); PG8_STAGE(PG8_SB(1, 0), b3, voffB); PG8_STAGE(PG8_SB(1, 1), b3 + hstep, voffB); PG8_STAGE(PG8_SA(1, 0), a3, voffA);
;             PG8_WAIT_V(8); PG8_WAIT_L(0); PG8_BAR; PG8_MMA(1, 0, At, B0); PG8_MMA(1, 1, At, B1); PG8_BAR; PG8_SCHED;
	s_waitcnt lgkmcnt(0)
	v_mfma_f32_16x16x32_bf16 v[124:127], v[128:131], v[178:181], v[124:127]
	v_mfma_f32_16x16x32_bf16 v[120:123], v[136:139], v[178:181], v[120:123]
	v_mfma_f32_16x16x32_bf16 v[108:111], v[128:131], v[186:189], v[108:111]
	v_mfma_f32_16x16x32_bf16 v[104:107], v[136:139], v[186:189], v[104:107]
	v_mfma_f32_16x16x32_bf16 v[92:95], v[128:131], v[194:197], v[92:95]
	v_mfma_f32_16x16x32_bf16 v[88:91], v[136:139], v[194:197], v[88:91]
	v_mfma_f32_16x16x32_bf16 v[76:79], v[128:131], v[210:213], v[76:79]
	v_mfma_f32_16x16x32_bf16 v[72:75], v[136:139], v[210:213], v[72:75]
	v_mfma_f32_16x16x32_bf16 v[124:127], v[132:135], v[182:185], v[124:127]
	v_mfma_f32_16x16x32_bf16 v[120:123], v[140:143], v[182:185], v[120:123]
	v_mfma_f32_16x16x32_bf16 v[108:111], v[132:135], v[190:193], v[108:111]
	v_mfma_f32_16x16x32_bf16 v[104:107], v[140:143], v[190:193], v[104:107]
	v_mfma_f32_16x16x32_bf16 v[92:95], v[132:135], v[206:209], v[92:95]
	v_mfma_f32_16x16x32_bf16 v[88:91], v[140:143], v[206:209], v[88:91]
	v_mfma_f32_16x16x32_bf16 v[76:79], v[132:135], v[214:217], v[76:79]
	v_mfma_f32_16x16x32_bf16 v[72:75], v[140:143], v[214:217], v[72:75]
	s_setprio 0
	s_setprio 1
	v_mfma_f32_16x16x32_bf16 v[116:119], v[144:147], v[178:181], v[116:119]
	v_mfma_f32_16x16x32_bf16 v[112:115], v[152:155], v[178:181], v[112:115]
	v_mfma_f32_16x16x32_bf16 v[100:103], v[144:147], v[186:189], v[100:103]
	v_mfma_f32_16x16x32_bf16 v[96:99], v[152:155], v[186:189], v[96:99]
	v_mfma_f32_16x16x32_bf16 v[84:87], v[144:147], v[194:197], v[84:87]
	v_mfma_f32_16x16x32_bf16 v[80:83], v[152:155], v[194:197], v[80:83]
	v_mfma_f32_16x16x32_bf16 v[68:71], v[144:147], v[210:213], v[68:71]
	v_mfma_f32_16x16x32_bf16 v[64:67], v[152:155], v[210:213], v[64:67]
	v_mfma_f32_16x16x32_bf16 v[116:119], v[148:151], v[182:185], v[116:119]
	v_mfma_f32_16x16x32_bf16 v[112:115], v[156:159], v[182:185], v[112:115]
	v_mfma_f32_16x16x32_bf16 v[100:103], v[148:151], v[190:193], v[100:103]
	v_mfma_f32_16x16x32_bf16 v[96:99], v[156:159], v[190:193], v[96:99]
	v_mfma_f32_16x16x32_bf16 v[84:87], v[148:151], v[206:209], v[84:87]
	v_mfma_f32_16x16x32_bf16 v[80:83], v[156:159], v[206:209], v[80:83]
	v_mfma_f32_16x16x32_bf16 v[68:71], v[148:151], v[214:217], v[68:71]
	s_setprio 3
	s_barrier
	v_mfma_f32_16x16x32_bf16 v[64:67], v[156:159], v[214:217], v[64:67]
	s_setprio 0
	s_add_i32 s63, s55, s42
	s_mov_b32 m0, s63
	ds_read_b128 v[178:181], v204 offset:16384
	ds_read_b128 v[182:185], v204 offset:17408
	ds_read_b128 v[186:189], v204 offset:18432
	ds_read_b128 v[190:193], v204 offset:19456
	ds_read_b128 v[194:197], v204 offset:20480
	ds_read_b128 v[206:209], v204 offset:21504
	ds_read_b128 v[210:213], v204 offset:22528
	ds_read_b128 v[214:217], v204 offset:23552
	v_lshl_add_u32 v229, s2, 8, v198
	v_lshl_or_b32 v228, s58, 8, v201
	v_lshlrev_b32_e32 v228, 1, v228
	v_lshl_add_u32 v228, v229, 11, v228
	s_add_u32 s84, s20, 0x0
	s_addc_u32 s85, s21, 0
	global_load_lds_dwordx4 v228, s[84:85]
	s_add_i32 m0, s63, 0x2000
	s_add_u32 s64, s6, 0x40000
	s_addc_u32 s65, s7, 0
	s_add_i32 s63, s56, s42
	s_add_u32 s84, s8, 0x0
	s_addc_u32 s85, s9, 0
	global_load_lds_dwordx4 v228, s[84:85]
	s_mov_b32 m0, s63
	s_add_u32 s84, s8, 0x100
	s_addc_u32 s85, s9, 0
	global_load_lds_dwordx4 v228, s[84:85]
	s_add_i32 m0, s63, 0x2000
	s_nop 0
	s_add_u32 s84, s20, 0x100
	s_addc_u32 s85, s21, 0
	global_load_lds_dwordx4 v228, s[84:85]
	s_mov_b32 m0, s44
	s_nop 0
	s_add_u32 s84, s8, 0x8000
	s_addc_u32 s85, s9, 0
	global_load_lds_dwordx4 v228, s[84:85]
	s_mov_b32 m0, s45
	s_nop 0
	s_add_u32 s84, s20, 0x8000
	s_addc_u32 s85, s21, 0
	global_load_lds_dwordx4 v228, s[84:85]
	s_waitcnt vmcnt(8)
	v_lshlrev_b32_e32 v226, 6, v229
	v_mov_b32_e32 v227, 0
	v_lshl_add_u64 v[226:227], v[168:169], 0, v[226:227]
	global_load_dwordx4 v[218:221], v[226:227], off
	global_load_dwordx4 v[222:225], v[226:227], off offset:1024
	global_load_dwordx4 v[230:233], v[226:227], off offset:2048
	global_load_dwordx4 v[234:237], v[226:227], off offset:3072
	s_mov_b32 s86, 0x2000
	s_mov_b32 s87, 0
	v_lshl_add_u64 v[226:227], v[226:227], 0, s[86:87]
	global_load_dwordx4 v[246:249], v[226:227], off
	global_load_dwordx4 v[252:255], v[226:227], off offset:1024
	global_load_dwordx4 v[238:241], v[226:227], off offset:2048
	global_load_dwordx4 v[242:245], v[226:227], off offset:3072
	s_waitcnt lgkmcnt(0)
	s_setprio 1
	s_barrier
	s_waitcnt lgkmcnt(0)
	v_mfma_f32_16x16x32_bf16 v[60:63], v[128:131], v[178:181], v[60:63]
	v_mfma_f32_16x16x32_bf16 v[56:59], v[136:139], v[178:181], v[56:59]
	v_mfma_f32_16x16x32_bf16 v[44:47], v[128:131], v[186:189], v[44:47]
	v_mfma_f32_16x16x32_bf16 v[40:43], v[136:139], v[186:189], v[40:43]
	v_mfma_f32_16x16x32_bf16 v[28:31], v[128:131], v[194:197], v[28:31]
	v_mfma_f32_16x16x32_bf16 v[24:27], v[136:139], v[194:197], v[24:27]
	v_mfma_f32_16x16x32_bf16 v[12:15], v[128:131], v[210:213], v[12:15]
	v_mfma_f32_16x16x32_bf16 v[8:11], v[136:139], v[210:213], v[8:11]
	v_mfma_f32_16x16x32_bf16 v[60:63], v[132:135], v[182:185], v[60:63]
	v_mfma_f32_16x16x32_bf16 v[56:59], v[140:143], v[182:185], v[56:59]
	v_mfma_f32_16x16x32_bf16 v[44:47], v[132:135], v[190:193], v[44:47]
	v_mfma_f32_16x16x32_bf16 v[40:43], v[140:143], v[190:193], v[40:43]
	v_mfma_f32_16x16x32_bf16 v[28:31], v[132:135], v[206:209], v[28:31]
	v_mfma_f32_16x16x32_bf16 v[24:27], v[140:143], v[206:209], v[24:27]
	v_mfma_f32_16x16x32_bf16 v[12:15], v[132:135], v[214:217], v[12:15]
	v_mfma_f32_16x16x32_bf16 v[8:11], v[140:143], v[214:217], v[8:11]
	s_setprio 0
	s_setprio 1
	v_mfma_f32_16x16x32_bf16 v[52:55], v[144:147], v[178:181], v[52:55]
	v_mfma_f32_16x16x32_bf16 v[48:51], v[152:155], v[178:181], v[48:51]
	v_mfma_f32_16x16x32_bf16 v[36:39], v[144:147], v[186:189], v[36:39]
	v_mfma_f32_16x16x32_bf16 v[32:35], v[152:155], v[186:189], v[32:35]
	v_mfma_f32_16x16x32_bf16 v[20:23], v[144:147], v[194:197], v[20:23]
	v_mfma_f32_16x16x32_bf16 v[16:19], v[152:155], v[194:197], v[16:19]
	v_mfma_f32_16x16x32_bf16 v[4:7], v[144:147], v[210:213], v[4:7]
	v_mfma_f32_16x16x32_bf16 v[0:3], v[152:155], v[210:213], v[0:3]
	v_mfma_f32_16x16x32_bf16 v[52:55], v[148:151], v[182:185], v[52:55]
	v_mfma_f32_16x16x32_bf16 v[48:51], v[156:159], v[182:185], v[48:51]
	v_mfma_f32_16x16x32_bf16 v[36:39], v[148:151], v[190:193], v[36:39]
	v_mfma_f32_16x16x32_bf16 v[32:35], v[156:159], v[190:193], v[32:35]
	v_mfma_f32_16x16x32_bf16 v[20:23], v[148:151], v[206:209], v[20:23]
	v_mfma_f32_16x16x32_bf16 v[16:19], v[156:159], v[206:209], v[16:19]
	v_mfma_f32_16x16x32_bf16 v[4:7], v[148:151], v[214:217], v[4:7]
	s_setprio 3
	s_barrier
; #define PG8_STAGE(bufoff, gbase, voff) do { _Pragma("unroll") for (int _i = 0; _i < 2; ++_i) \
;         __builtin_amdgcn_global_load_lds((const unsigned*)((const char*)(gbase) + (voff)[_i]), (PG8_LAS unsigned*)(lds + (bufoff) + ldsw + _i * 8192), 16, 0, 0); } while (0)
; #define PG8_LDA(dst, b, h) do { _Pragma("unroll") for (int m = 0; m < 4; ++m) _Pragma("unroll") for (int k = 0; k < 2; ++k) dst[m][k] = *(const PG8_LAS bf16x8*)(lds + PG8_SA(b, h) + aoff + m * 2048 + k * 1024); } while (0)
; #define PG8_LDB(dst, b, h) do { _Pragma("unroll") for (int n = 0; n < 2; ++n) _Pragma("unroll") for (int k = 0; k < 2; ++k) dst[n][k] = *(const PG8_LAS bf16x8*)(lds + PG8_SB(b, h) + boff + n * 2048 + k * 1024); } while (0)
; #define PG8_MMA(ai, bj, At, Bt) do { __builtin_amdgcn_s_setprio(1); _Pragma("unroll") for (int m = 0; m < 4; ++m) _Pragma("unroll") for (int n = 0; n < 2; ++n) _Pragma("unroll") for (int k = 0; k < 2; ++k) \
;         acc[ai][bj][m][n] = __builtin_amdgcn_mfma_f32_16x16x32_bf16(Bt[n][k], At[m][k], acc[ai][bj][m][n], 0, 0, 0); __builtin_amdgcn_s_setprio(0); } while (0)
; #define PG8_WAIT_V(n) asm volatile("s_waitcnt vmcnt(" #n ")" ::: "memory")
; template <class Epi, class Sched, bool ALIGN_EPI = false, bool SP2 = false>
; __device__ __forceinline__ void gemm_phase(PG8_LAS unsigned char* lds, const Gemm g, const Sched& S, const Epi& E) {
;     ...
;             PG8_LDB(B0, 0, 0); PG8_LDB(B1, 0, 1); PG8_SCHED; PG8_LDA(At, 0, 0); PG8_STAGE(PG8_SA(1, 1), a1 + hstep, voffA);
;             PG8_WAIT_V(8); PG8_WAIT_L(0); PG8_BAR; PG8_MMA(0, 0, At, B0); PG8_MMA(0, 1, At, B1); PG8_BAR; PG8_SCHED;
;             PG8_LDA(At, 0, 1); PG8_STAGE(PG8_SB(0, 0), b2, voffB); PG8_STAGE(PG8_SB(0, 1), b2 + hstep, voffB); PG8_STAGE(PG8_SA(0, 0), a2, voffA);
;             PG8_WAIT_V(8); PG8_WAIT_L(0); PG8_BAR; PG8_MMA(1, 0, At, B0); PG8_MMA(1, 1, At, B1); PG8_BAR; PG8_SCHED;
;             PG8_LDB(B0, 1, 0); PG8_LDB(B1, 1, 1); PG8_SCHED; PG8_LDA(At, 1, 0); PG8_STAGE(PG8_SA(0, 1), a2 + hstep, voffA);
;             PG8_WAIT_V(8); PG8_WAIT_L(0); PG8_BAR; PG8_MMA(0, 0, At, B0); PG8_MMA(0, 1, At, B1); PG8_BAR; PG8_SCHED;
;             PG8_LDA(At, 1, 1); PG8_STAGE(PG8_SB(1, 0), b3, voffB); PG8_STAGE(PG8_SB(1, 1), b3 + hstep, voffB); PG8_STAGE(PG8_SA(1, 0), a3, voffA);
;             PG8_WAIT_V(8); PG8_WAIT_L(0); PG8_BAR; PG8_MMA(1, 0, At, B0); PG8_MMA(1, 1, At, B1); PG8_BAR; PG8_SCHED;
	v_mfma_f32_16x16x32_bf16 v[0:3], v[156:159], v[214:217], v[0:3]
	s_setprio 0
	s_add_i32 s63, 0, 0x18000
	s_add_i32 s64, 0, 0x1c000
	v_add_u32_e32 v140, s63, v199
	v_add_u32_e32 v156, s64, v199
	ds_read_b128 v[128:131], v140
	ds_read_b128 v[132:135], v140 offset:1024
	ds_read_b128 v[136:139], v140 offset:2048
	ds_read_b128 v[140:143], v140 offset:3072
	ds_read_b128 v[144:147], v156
	ds_read_b128 v[148:151], v156 offset:1024
	ds_read_b128 v[152:155], v156 offset:2048
	ds_read_b128 v[156:159], v156 offset:3072
	s_add_u32 s40, s40, 0x40000
	s_addc_u32 s41, s41, 0
	s_mov_b32 m0, s46
	ds_read_b128 v[178:181], v204 offset:32768
	ds_read_b128 v[182:185], v204 offset:33792
	ds_read_b128 v[186:189], v204 offset:34816
	ds_read_b128 v[190:193], v204 offset:35840
	ds_read_b128 v[194:197], v204 offset:36864
	ds_read_b128 v[206:209], v204 offset:37888
	ds_read_b128 v[210:213], v204 offset:38912
	ds_read_b128 v[214:217], v204 offset:39936
	s_add_u32 s84, s8, 0x10000
	s_addc_u32 s85, s9, 0
	global_load_lds_dwordx4 v228, s[84:85]
	s_mov_b32 m0, s47
	s_nop 0
	s_add_u32 s84, s20, 0x10000
	s_addc_u32 s85, s21, 0
	global_load_lds_dwordx4 v228, s[84:85]
	s_waitcnt vmcnt(16)
	s_waitcnt lgkmcnt(0)
	s_setprio 1
	s_barrier
	s_waitcnt lgkmcnt(0)
	v_mfma_f32_16x16x32_bf16 v[124:127], v[128:131], v[178:181], v[124:127]
	v_mfma_f32_16x16x32_bf16 v[120:123], v[136:139], v[178:181], v[120:123]
	v_mfma_f32_16x16x32_bf16 v[108:111], v[128:131], v[186:189], v[108:111]
	v_mfma_f32_16x16x32_bf16 v[104:107], v[136:139], v[186:189], v[104:107]
	v_mfma_f32_16x16x32_bf16 v[92:95], v[128:131], v[194:197], v[92:95]
	v_mfma_f32_16x16x32_bf16 v[88:91], v[136:139], v[194:197], v[88:91]
	v_mfma_f32_16x16x32_bf16 v[76:79], v[128:131], v[210:213], v[76:79]
	v_mfma_f32_16x16x32_bf16 v[72:75], v[136:139], v[210:213], v[72:75]
	v_mfma_f32_16x16x32_bf16 v[124:127], v[132:135], v[182:185], v[124:127]
	v_mfma_f32_16x16x32_bf16 v[120:123], v[140:143], v[182:185], v[120:123]
	v_mfma_f32_16x16x32_bf16 v[108:111], v[132:135], v[190:193], v[108:111]
	v_mfma_f32_16x16x32_bf16 v[104:107], v[140:143], v[190:193], v[104:107]
	v_mfma_f32_16x16x32_bf16 v[92:95], v[132:135], v[206:209], v[92:95]
	v_mfma_f32_16x16x32_bf16 v[88:91], v[140:143], v[206:209], v[88:91]
	v_mfma_f32_16x16x32_bf16 v[76:79], v[132:135], v[214:217], v[76:79]
	v_mfma_f32_16x16x32_bf16 v[72:75], v[140:143], v[214:217], v[72:75]
	s_setprio 0
	s_setprio 1
	v_mfma_f32_16x16x32_bf16 v[116:119], v[144:147], v[178:181], v[116:119]
	v_mfma_f32_16x16x32_bf16 v[112:115], v[152:155], v[178:181], v[112:115]
	v_mfma_f32_16x16x32_bf16 v[100:103], v[144:147], v[186:189], v[100:103]
	v_mfma_f32_16x16x32_bf16 v[96:99], v[152:155], v[186:189], v[96:99]
	v_mfma_f32_16x16x32_bf16 v[84:87], v[144:147], v[194:197], v[84:87]
	v_mfma_f32_16x16x32_bf16 v[80:83], v[152:155], v[194:197], v[80:83]
	v_mfma_f32_16x16x32_bf16 v[68:71], v[144:147], v[210:213], v[68:71]
	v_mfma_f32_16x16x32_bf16 v[64:67], v[152:155], v[210:213], v[64:67]
	v_mfma_f32_16x16x32_bf16 v[116:119], v[148:151], v[182:185], v[116:119]
	v_mfma_f32_16x16x32_bf16 v[112:115], v[156:159], v[182:185], v[112:115]
	v_mfma_f32_16x16x32_bf16 v[100:103], v[148:151], v[190:193], v[100:103]
	v_mfma_f32_16x16x32_bf16 v[96:99], v[156:159], v[190:193], v[96:99]
	v_mfma_f32_16x16x32_bf16 v[84:87], v[148:151], v[206:209], v[84:87]
	v_mfma_f32_16x16x32_bf16 v[80:83], v[156:159], v[206:209], v[80:83]
	v_mfma_f32_16x16x32_bf16 v[68:71], v[148:151], v[214:217], v[68:71]
	s_setprio 3
	s_barrier
; #define PG8_STAGE(bufoff, gbase, voff) do { _Pragma("unroll") for (int _i = 0; _i < 2; ++_i) \
;         __builtin_amdgcn_global_load_lds((const unsigned*)((const char*)(gbase) + (voff)[_i]), (PG8_LAS unsigned*)(lds + (bufoff) + ldsw + _i * 8192), 16, 0, 0); } while (0)
; #define PG8_LDA(dst, b, h) do { _Pragma("unroll") for (int m = 0; m < 4; ++m) _Pragma("unroll") for (int k = 0; k < 2; ++k) dst[m][k] = *(const PG8_LAS bf16x8*)(lds + PG8_SA(b, h) + aoff + m * 2048 + k * 1024); } while (0)
; #define PG8_LDB(dst, b, h) do { _Pragma("unroll") for (int n = 0; n < 2; ++n) _Pragma("unroll") for (int k = 0; k < 2; ++k) dst[n][k] = *(const PG8_LAS bf16x8*)(lds + PG8_SB(b, h) + boff + n * 2048 + k * 1024); } while (0)
; #define PG8_MMA(ai, bj, At, Bt) do { __builtin_amdgcn_s_setprio(1); _Pragma("unroll") for (int m = 0; m < 4; ++m) _Pragma("unroll") for (int n = 0; n < 2; ++n) _Pragma("unroll") for (int k = 0; k < 2; ++k) \
;         acc[ai][bj][m][n] = __builtin_amdgcn_mfma_f32_16x16x32_bf16(Bt[n][k], At[m][k], acc[ai][bj][m][n], 0, 0, 0); __builtin_amdgcn_s_setprio(0); } while (0)
; #define PG8_WAIT_V(n) asm volatile("s_waitcnt vmcnt(" #n ")" ::: "memory")
; template <class Epi, class Sched, bool ALIGN_EPI = false, bool SP2 = false>
; __device__ __forceinline__ void gemm_phase(PG8_LAS unsigned char* lds, const Gemm g, const Sched& S, const Epi& E) {
;     ...
;             PG8_LDB(B0, 0, 0); PG8_LDB(B1, 0, 1); PG8_SCHED; PG8_LDA(At, 0, 0); PG8_STAGE(PG8_SA(1, 1), a1 + hstep, voffA);
;             PG8_WAIT_V(8); PG8_WAIT_L(0); PG8_BAR; PG8_MMA(0, 0, At, B0); PG8_MMA(0, 1, At, B1); PG8_BAR; PG8_SCHED;
;             PG8_LDA(At, 0, 1); PG8_STAGE(PG8_SB(0, 0), b2, voffB); PG8_STAGE(PG8_SB(0, 1), b2 + hstep, voffB); PG8_STAGE(PG8_SA(0, 0), a2, voffA);
;             PG8_WAIT_V(8); PG8_WAIT_L(0); PG8_BAR; PG8_MMA(1, 0, At, B0); PG8_MMA(1, 1, At, B1); PG8_BAR; PG8_SCHED;
;             PG8_LDB(B0, 1, 0); PG8_LDB(B1, 1, 1); PG8_SCHED; PG8_LDA(At, 1, 0); PG8_STAGE(PG8_SA(0, 1), a2 + hstep, voffA);
;             PG8_WAIT_V(8); PG8_WAIT_L(0); PG8_BAR; PG8_MMA(0, 0, At, B0); PG8_MMA(0, 1, At, B1); PG8_BAR; PG8_SCHED;
;             PG8_LDA(At, 1, 1); PG8_STAGE(PG8_SB(1, 0), b3, voffB); PG8_STAGE(PG8_SB(1, 1), b3 + hstep, voffB); PG8_STAGE(PG8_SA(1, 0), a3, voffA);
;             PG8_WAIT_V(8); PG8_WAIT_L(0); PG8_BAR; PG8_MMA(1, 0, At, B0); PG8_MMA(1, 1, At, B1); PG8_BAR; PG8_SCHED;
	v_mfma_f32_16x16x32_bf16 v[64:67], v[156:159], v[214:217], v[64:67]
	s_setprio 0
	s_add_i32 s40, s63, s42
	s_mov_b32 m0, s40
	ds_read_b128 v[178:181], v204 offset:49152
	ds_read_b128 v[182:185], v204 offset:50176
	ds_read_b128 v[186:189], v204 offset:51200
	ds_read_b128 v[190:193], v204 offset:52224
	ds_read_b128 v[194:197], v204 offset:53248
	ds_read_b128 v[206:209], v204 offset:54272
	ds_read_b128 v[210:213], v204 offset:55296
	ds_read_b128 v[214:217], v204 offset:56320
	s_add_u32 s84, s8, 0x18000
	s_addc_u32 s85, s9, 0
	global_load_lds_dwordx4 v228, s[84:85]
	s_add_i32 m0, s40, 0x2000
	s_add_u32 s6, s6, 0x40080
	s_addc_u32 s7, s7, 0
	s_add_i32 s40, s64, s42
	s_add_u32 s84, s20, 0x18000
	s_addc_u32 s85, s21, 0
	global_load_lds_dwordx4 v228, s[84:85]
	s_mov_b32 m0, s40
	s_nop 0
	s_add_u32 s84, s8, 0x8100
	s_addc_u32 s85, s9, 0
	global_load_lds_dwordx4 v228, s[84:85]
	s_add_i32 m0, s40, 0x2000
	s_nop 0
	s_add_u32 s84, s20, 0x8100
	s_addc_u32 s85, s21, 0
	global_load_lds_dwordx4 v228, s[84:85]
	s_mov_b32 m0, s52
	s_nop 0
	s_add_u32 s84, s8, 0x10100
	s_addc_u32 s85, s9, 0
	global_load_lds_dwordx4 v228, s[84:85]
	s_mov_b32 m0, s53
	s_nop 0
	s_add_u32 s84, s20, 0x10100
	s_addc_u32 s85, s21, 0
	global_load_lds_dwordx4 v228, s[84:85]
	s_waitcnt vmcnt(8)
	s_waitcnt lgkmcnt(0)
	s_setprio 1
	s_barrier
	s_waitcnt lgkmcnt(0)
	v_mfma_f32_16x16x32_bf16 v[60:63], v[128:131], v[178:181], v[60:63]
	v_mfma_f32_16x16x32_bf16 v[56:59], v[136:139], v[178:181], v[56:59]
	v_mfma_f32_16x16x32_bf16 v[44:47], v[128:131], v[186:189], v[44:47]
	v_mfma_f32_16x16x32_bf16 v[40:43], v[136:139], v[186:189], v[40:43]
	v_mfma_f32_16x16x32_bf16 v[28:31], v[128:131], v[194:197], v[28:31]
	v_mfma_f32_16x16x32_bf16 v[24:27], v[136:139], v[194:197], v[24:27]
	v_mfma_f32_16x16x32_bf16 v[12:15], v[128:131], v[210:213], v[12:15]
	v_mfma_f32_16x16x32_bf16 v[8:11], v[136:139], v[210:213], v[8:11]
	v_mfma_f32_16x16x32_bf16 v[60:63], v[132:135], v[182:185], v[60:63]
	v_mfma_f32_16x16x32_bf16 v[56:59], v[140:143], v[182:185], v[56:59]
	v_mfma_f32_16x16x32_bf16 v[44:47], v[132:135], v[190:193], v[44:47]
	v_mfma_f32_16x16x32_bf16 v[40:43], v[140:143], v[190:193], v[40:43]
	v_mfma_f32_16x16x32_bf16 v[28:31], v[132:135], v[206:209], v[28:31]
	v_mfma_f32_16x16x32_bf16 v[24:27], v[140:143], v[206:209], v[24:27]
	v_mfma_f32_16x16x32_bf16 v[12:15], v[132:135], v[214:217], v[12:15]
	v_mfma_f32_16x16x32_bf16 v[8:11], v[140:143], v[214:217], v[8:11]
	s_setprio 0
	s_setprio 1
	v_mfma_f32_16x16x32_bf16 v[52:55], v[144:147], v[178:181], v[52:55]
	v_mfma_f32_16x16x32_bf16 v[48:51], v[152:155], v[178:181], v[48:51]
	v_mfma_f32_16x16x32_bf16 v[36:39], v[144:147], v[186:189], v[36:39]
	v_mfma_f32_16x16x32_bf16 v[32:35], v[152:155], v[186:189], v[32:35]
	v_mfma_f32_16x16x32_bf16 v[20:23], v[144:147], v[194:197], v[20:23]
	v_mfma_f32_16x16x32_bf16 v[16:19], v[152:155], v[194:197], v[16:19]
	v_mfma_f32_16x16x32_bf16 v[4:7], v[144:147], v[210:213], v[4:7]
	v_mfma_f32_16x16x32_bf16 v[0:3], v[152:155], v[210:213], v[0:3]
	v_mfma_f32_16x16x32_bf16 v[52:55], v[148:151], v[182:185], v[52:55]
	v_mfma_f32_16x16x32_bf16 v[48:51], v[156:159], v[182:185], v[48:51]
	v_mfma_f32_16x16x32_bf16 v[36:39], v[148:151], v[190:193], v[36:39]
	v_mfma_f32_16x16x32_bf16 v[32:35], v[156:159], v[190:193], v[32:35]
	v_mfma_f32_16x16x32_bf16 v[20:23], v[148:151], v[206:209], v[20:23]
	v_mfma_f32_16x16x32_bf16 v[16:19], v[156:159], v[206:209], v[16:19]
	v_mfma_f32_16x16x32_bf16 v[4:7], v[148:151], v[214:217], v[4:7]
	s_setprio 3
	s_barrier
	v_mfma_f32_16x16x32_bf16 v[0:3], v[156:159], v[214:217], v[0:3]
	s_setprio 0
	s_add_i32 s62, s62, 2
	s_add_u32 s4, s4, 0x100
	s_addc_u32 s5, s5, 0
	s_add_u32 s60, s60, 0x100
	s_addc_u32 s61, s61, 0
	s_mov_b32 s32, 1
	s_branch .Lp6x_done

; __device__ __forceinline__ void row_rstd8(const float* SS, int row0, int fq, float (&rs)[2][4]) {
; #pragma unroll
;     for (int ai = 0; ai < 2; ++ai)
; #pragma unroll
;         for (int m = 0; m < 4; ++m) { const f32x4 t = *(const f32x4*)(SS + (size_t)(row0 + ai * HALF + m * 16) * 16 + 4 * fq); rs[ai][m] = (t[0] + t[1]) + (t[2] + t[3]); }
;     __device__ __forceinline__ void operator()(const f32x4 (&acc)[2][2][4][2], const Unit& u, int wr, int wc, int fr, int fq) const {
;     ...
;         if (u.pm == rtab_pm) {
; #pragma unroll
;             for (int ai = 0; ai < 2; ++ai)
; #pragma unroll
;                 for (int m = 0; m < 4; ++m) rs[ai][m] = rtab[wr * 64 + fr + ai * HALF + m * 16];
;         } else row_rstd8(SS, row0, fq, rs);
.LBB0_1036:
	v_lshl_add_u32 v134, s2, 8, v198
	v_lshl_or_b32 v250, s58, 8, v201
	v_lshlrev_b32_e32 v250, 1, v250
	v_lshl_add_u32 v250, v134, 11, v250
	v_or_b32_e32 v132, 16, v134
	v_or_b32_e32 v130, 32, v134
	v_or_b32_e32 v128, 48, v134
	s_cmp_lg_u32 s2, s17
	v_ashrrev_i32_e32 v133, 31, v132
	s_mov_b64 s[2:3], -1
	v_ashrrev_i32_e32 v135, 31, v134
	v_ashrrev_i32_e32 v131, 31, v130
	v_ashrrev_i32_e32 v129, 31, v128
	v_add_u32_e32 v136, 0x80, v134
	s_cbranch_scc0 .LBB0_1038
	s_cmp_lg_u32 s32, 0
	s_cbranch_scc1 .Lp6x_rsf
	v_lshlrev_b64 v[138:139], 6, v[134:135]
	v_lshlrev_b64 v[142:143], 6, v[132:133]
	v_lshl_add_u64 v[154:155], v[168:169], 0, v[138:139]
	v_lshl_add_u64 v[142:143], v[168:169], 0, v[142:143]
	v_lshlrev_b64 v[146:147], 6, v[130:131]
	global_load_dwordx4 v[138:141], v[154:155], off
	v_lshl_add_u64 v[146:147], v[168:169], 0, v[146:147]
	global_load_dwordx4 v[142:145], v[142:143], off
	v_lshlrev_b64 v[150:151], 6, v[128:129]
	global_load_dwordx4 v[146:149], v[146:147], off
	v_lshl_add_u64 v[150:151], v[168:169], 0, v[150:151]
	global_load_dwordx4 v[150:153], v[150:151], off
	v_add_u32_e32 v182, 0x80, v134
	v_ashrrev_i32_e32 v183, 31, v182
	v_add_co_u32_e32 v158, vcc, s48, v154
	v_lshlrev_b64 v[184:185], 6, v[182:183]
	s_nop 0
	v_addc_co_u32_e32 v159, vcc, 0, v155, vcc
	v_lshl_add_u64 v[184:185], v[168:169], 0, v[184:185]
	global_load_dwordx4 v[154:157], v[158:159], off offset:2048
	global_load_dwordx4 v[178:181], v[158:159], off offset:3072
	s_nop 0
	global_load_dwordx4 v[184:187], v[184:185], off
	s_nop 0
	global_load_dwordx4 v[188:191], v[158:159], off offset:1024
	v_mov_b64_e32 v[158:159], s[18:19]
	s_waitcnt vmcnt(0)
	s_branch .Lp6x_rsj
.Lp6x_rsf:
	v_lshlrev_b64 v[138:139], 6, v[134:135]
	v_lshlrev_b64 v[142:143], 6, v[132:133]
	v_lshl_add_u64 v[154:155], v[168:169], 0, v[138:139]
	v_lshl_add_u64 v[142:143], v[168:169], 0, v[142:143]
	v_lshlrev_b64 v[146:147], 6, v[130:131]
	v_lshl_add_u64 v[146:147], v[168:169], 0, v[146:147]
	v_lshlrev_b64 v[150:151], 6, v[128:129]
	v_lshl_add_u64 v[150:151], v[168:169], 0, v[150:151]
	v_add_u32_e32 v182, 0x80, v134
	v_ashrrev_i32_e32 v183, 31, v182
	v_add_co_u32_e32 v158, vcc, s48, v154
	v_lshlrev_b64 v[184:185], 6, v[182:183]
	s_nop 0
	v_addc_co_u32_e32 v159, vcc, 0, v155, vcc
	v_lshl_add_u64 v[184:185], v[168:169], 0, v[184:185]
	s_nop 0
	s_nop 0
	v_mov_b64_e32 v[158:159], s[18:19]
	s_waitcnt vmcnt(6)
	v_mov_b32_e32 v138, v218
	v_mov_b32_e32 v139, v219
	v_mov_b32_e32 v140, v220
	v_mov_b32_e32 v141, v221
	v_mov_b32_e32 v142, v222
	v_mov_b32_e32 v143, v223
	v_mov_b32_e32 v144, v224
	v_mov_b32_e32 v145, v225
	v_mov_b32_e32 v146, v230
	v_mov_b32_e32 v147, v231
	v_mov_b32_e32 v148, v232
	v_mov_b32_e32 v149, v233
	v_mov_b32_e32 v150, v234
	v_mov_b32_e32 v151, v235
	v_mov_b32_e32 v152, v236
	v_mov_b32_e32 v153, v237
	v_mov_b32_e32 v154, v238
	v_mov_b32_e32 v155, v239
	v_mov_b32_e32 v156, v240
	v_mov_b32_e32 v157, v241
	v_mov_b32_e32 v178, v242
	v_mov_b32_e32 v179, v243
	v_mov_b32_e32 v180, v244
	v_mov_b32_e32 v181, v245
	v_mov_b32_e32 v184, v246
	v_mov_b32_e32 v185, v247
	v_mov_b32_e32 v186, v248
	v_mov_b32_e32 v187, v249
	v_mov_b32_e32 v188, v252
	v_mov_b32_e32 v189, v253
	v_mov_b32_e32 v190, v254
	v_mov_b32_e32 v191, v255
; __device__ __forceinline__ void row_rstd8(const float* SS, int row0, int fq, float (&rs)[2][4]) {
;     ...
;         for (int m = 0; m < 4; ++m) { const f32x4 t = *(const f32x4*)(SS + (size_t)(row0 + ai * HALF + m * 16) * 16 + 4 * fq); rs[ai][m] = (t[0] + t[1]) + (t[2] + t[3]); }
; #pragma unroll
;     for (int ai = 0; ai < 2; ++ai)
; #pragma unroll
;         for (int m = 0; m < 4; ++m) { float v = sum_fq(rs[ai][m]); rs[ai][m] = rsqrtf(v * (1.f / DM) + EPS); }
.Lp6x_rsj:
	v_mov_b32_e32 v192, v139
	v_mov_b32_e32 v193, v140
	v_mov_b32_e32 v139, v141
	v_mov_b32_e32 v140, v143
	v_mov_b32_e32 v141, v144
	v_mov_b32_e32 v143, v145
	v_mov_b32_e32 v144, v147
	v_mov_b32_e32 v145, v148
	v_mov_b32_e32 v147, v149
	v_pk_add_f32 v[138:139], v[192:193], v[138:139]
	v_pk_add_f32 v[140:141], v[140:141], v[142:143]
	v_pk_add_f32 v[142:143], v[144:145], v[146:147]
	v_pk_add_f32 v[138:139], v[138:139], v[138:139] op_sel:[0,1] op_sel_hi:[1,0]
	v_pk_add_f32 v[140:141], v[140:141], v[140:141] op_sel:[0,1] op_sel_hi:[1,0]
	v_pk_add_f32 v[142:143], v[142:143], v[142:143] op_sel:[0,1] op_sel_hi:[1,0]
	v_mov_b32_e32 v137, v138
	v_mov_b32_e32 v141, v140
	v_mov_b32_e32 v143, v142
	v_permlane32_swap_b32_e32 v138, v137
	v_permlane32_swap_b32_e32 v140, v141
	v_permlane32_swap_b32_e32 v142, v143
	v_add_f32_e32 v139, v138, v137
	v_add_f32_e32 v138, v140, v141
	v_add_f32_e32 v141, v142, v143
	v_mov_b32_e32 v143, v139
	v_mov_b32_e32 v142, v138
	s_nop 0
	v_permlane16_swap_b32_e32 v139, v143
	v_permlane16_swap_b32_e32 v138, v142
	v_pk_add_f32 v[138:139], v[138:139], v[142:143]
	v_mov_b32_e32 v148, v151
	v_mov_b32_e32 v149, v152
	v_mov_b32_e32 v151, v153
	v_pk_fma_f32 v[138:139], v[138:139], s[16:17], v[158:159] op_sel_hi:[1,0,0]
	v_pk_add_f32 v[144:145], v[148:149], v[150:151]
	v_mul_f32_e32 v137, 0x4b800000, v139
	v_cmp_gt_f32_e32 vcc, s57, v139
	v_pk_add_f32 v[144:145], v[144:145], v[144:145] op_sel:[0,1] op_sel_hi:[1,0]
	v_mul_f32_e32 v140, 0x4b800000, v138
	v_cndmask_b32_e32 v137, v139, v137, vcc
	v_rsq_f32_e32 v139, v137
	v_mov_b32_e32 v137, v144
	v_cmp_gt_f32_e64 s[2:3], s57, v138
	s_nop 0
	v_permlane32_swap_b32_e32 v144, v137
	v_cndmask_b32_e64 v138, v138, v140, s[2:3]
	v_add_f32_e32 v140, v144, v137
	v_mov_b32_e32 v145, v141
	v_mov_b32_e32 v144, v140
	s_nop 0
	v_permlane16_swap_b32_e32 v141, v145
	v_permlane16_swap_b32_e32 v140, v144
	v_pk_add_f32 v[140:141], v[140:141], v[144:145]
	v_rsq_f32_e32 v138, v138
	v_pk_fma_f32 v[140:141], v[140:141], s[16:17], v[158:159] op_sel_hi:[1,0,0]
	v_mov_b32_e32 v150, v185
	v_mul_f32_e32 v137, 0x4b800000, v141
	v_cmp_gt_f32_e64 s[4:5], s57, v141
	v_cmp_gt_f32_e64 s[6:7], s57, v140
	v_mov_b32_e32 v151, v186
	v_cndmask_b32_e64 v137, v141, v137, s[4:5]
	v_rsq_f32_e32 v141, v137
	v_mul_f32_e32 v137, 0x4b800000, v140
	v_cndmask_b32_e64 v137, v140, v137, s[6:7]
	v_mov_b32_e32 v185, v187
	v_rsq_f32_e32 v140, v137
	v_pk_add_f32 v[150:151], v[150:151], v[184:185]
	v_mov_b32_e32 v152, v189
	v_mov_b32_e32 v153, v190
	v_mov_b32_e32 v189, v191
	v_pk_add_f32 v[150:151], v[150:151], v[150:151] op_sel:[0,1] op_sel_hi:[1,0]
	v_pk_add_f32 v[152:153], v[152:153], v[188:189]
	v_pk_mul_f32 v[142:143], v[138:139], s[22:23] op_sel_hi:[1,0]
	v_mov_b32_e32 v137, v150
	v_pk_add_f32 v[152:153], v[152:153], v[152:153] op_sel:[0,1] op_sel_hi:[1,0]
	v_cndmask_b32_e64 v195, v138, v142, s[2:3]
	v_cndmask_b32_e32 v194, v139, v143, vcc
	v_pk_mul_f32 v[138:139], v[140:141], s[22:23] op_sel_hi:[1,0]
	v_permlane32_swap_b32_e32 v150, v137
	v_cndmask_b32_e64 v188, v141, v139, s[4:5]
	v_add_f32_e32 v139, v150, v137
	v_mov_b32_e32 v137, v152
	s_nop 1
	v_permlane32_swap_b32_e32 v152, v137
	v_cndmask_b32_e64 v189, v140, v138, s[6:7]
	v_add_f32_e32 v138, v152, v137
	v_mov_b32_e32 v141, v139
	v_mov_b32_e32 v140, v138
	s_nop 0
	v_permlane16_swap_b32_e32 v139, v141
	v_permlane16_swap_b32_e32 v138, v140
	v_pk_add_f32 v[138:139], v[138:139], v[140:141]
	v_mov_b32_e32 v146, v155
	v_pk_fma_f32 v[138:139], v[138:139], s[16:17], v[158:159] op_sel_hi:[1,0,0]
	v_mov_b32_e32 v147, v156
	v_mul_f32_e32 v137, 0x4b800000, v139
	v_cmp_gt_f32_e32 vcc, s57, v139
	v_mov_b32_e32 v155, v157
	v_pk_add_f32 v[146:147], v[146:147], v[154:155]
	v_cndmask_b32_e32 v137, v139, v137, vcc
	v_rsq_f32_e32 v139, v137
	v_mul_f32_e32 v137, 0x4b800000, v138
	v_cmp_gt_f32_e64 s[2:3], s57, v138
	v_mov_b32_e32 v148, v179
	v_mov_b32_e32 v149, v180
	v_mov_b32_e32 v179, v181
	v_pk_add_f32 v[146:147], v[146:147], v[146:147] op_sel:[0,1] op_sel_hi:[1,0]
	v_cndmask_b32_e64 v137, v138, v137, s[2:3]
	v_pk_add_f32 v[148:149], v[148:149], v[178:179]
	v_rsq_f32_e32 v138, v137
	v_mov_b32_e32 v137, v146
	v_pk_add_f32 v[148:149], v[148:149], v[148:149] op_sel:[0,1] op_sel_hi:[1,0]
	s_nop 0
	v_permlane32_swap_b32_e32 v146, v137
	v_add_f32_e32 v141, v146, v137
	v_mov_b32_e32 v137, v148
	s_nop 1
	v_permlane32_swap_b32_e32 v148, v137
	v_add_f32_e32 v140, v148, v137
	v_mov_b32_e32 v143, v141
	v_mov_b32_e32 v142, v140
	s_nop 0
	v_permlane16_swap_b32_e32 v141, v143
	v_permlane16_swap_b32_e32 v140, v142
	v_pk_add_f32 v[140:141], v[140:141], v[142:143]
	v_pk_mul_f32 v[142:143], v[138:139], s[22:23] op_sel_hi:[1,0]
	v_pk_fma_f32 v[140:141], v[140:141], s[16:17], v[158:159] op_sel_hi:[1,0,0]
	v_cndmask_b32_e64 v181, v138, v142, s[2:3]
	v_mul_f32_e32 v137, 0x4b800000, v141
	v_cmp_gt_f32_e64 s[4:5], s57, v141
	v_cmp_gt_f32_e64 s[6:7], s57, v140
	v_cndmask_b32_e32 v180, v139, v143, vcc
	v_cndmask_b32_e64 v137, v141, v137, s[4:5]
	v_rsq_f32_e32 v141, v137
	v_mul_f32_e32 v137, 0x4b800000, v140
	v_cndmask_b32_e64 v137, v140, v137, s[6:7]
	v_rsq_f32_e32 v140, v137
	s_mov_b64 s[2:3], 0
	v_mov_b64_e32 v[184:185], v[182:183]
	v_pk_mul_f32 v[138:139], v[140:141], s[22:23] op_sel_hi:[1,0]
	s_nop 0
	v_cndmask_b32_e64 v179, v140, v138, s[6:7]
	v_cndmask_b32_e64 v178, v141, v139, s[4:5]
